# NSA: add sliding-window unmasked sub-tile fast path
# speedup vs baseline: 1.0125x; 1.0006x over previous
.LBB0_401:
	s_lshl_b32 s0, s1, 6
	s_or_b32 s2, s0, s90
	v_cmp_le_i32_e32 vcc, s2, v123
	s_and_saveexec_b64 s[74:75], vcc
	s_cbranch_execz .LBB0_400
	s_or_b32 s0, s2, 63
	v_cmp_ge_i32_e32 vcc, s0, v144
	s_and_saveexec_b64 s[76:77], vcc
	s_cbranch_execz .LBB0_399
	s_mul_i32 s91, s1, 0x2400
	v_readfirstlane_b32 s4, v176
	v_readfirstlane_b32 s5, v145
	s_nop 0
	s_cmp_le_i32 s0, s4
	s_cbranch_scc0 .Lnsa_win_slow
	s_cmp_ge_i32 s2, s5
	s_cbranch_scc0 .Lnsa_win_slow
	v_add_u32_e32 v1, s91, v177
	v_add_u32_e32 v179, s91, v178
	ds_read_b128 v[180:183], v1
	ds_read_b128 v[184:187], v1 offset:4608
	ds_read_b128 v[188:191], v1 offset:32
	ds_read_b128 v[192:195], v1 offset:4640
	ds_read_b128 v[196:199], v1 offset:64
	ds_read_b128 v[200:203], v1 offset:4672
	ds_read_b128 v[204:207], v1 offset:96
	ds_read_b128 v[208:211], v1 offset:4704
	v_mul_f32_e64 v88, -1.0, s81
	v_mov_b32_e32 v222, 0x3e38aa3b
	s_waitcnt lgkmcnt(6)
	v_mfma_f32_32x32x16_bf16 v[48:63], v[180:183], v[98:101], 0
	v_mfma_f32_32x32x16_bf16 v[64:79], v[184:187], v[98:101], 0
	s_waitcnt lgkmcnt(4)
	v_mfma_f32_32x32x16_bf16 v[48:63], v[188:191], v[102:105], v[48:63]
	v_mfma_f32_32x32x16_bf16 v[64:79], v[192:195], v[102:105], v[64:79]
	s_waitcnt lgkmcnt(2)
	v_mfma_f32_32x32x16_bf16 v[48:63], v[196:199], v[106:109], v[48:63]
	v_mfma_f32_32x32x16_bf16 v[64:79], v[200:203], v[106:109], v[64:79]
	s_waitcnt lgkmcnt(0)
	v_mfma_f32_32x32x16_bf16 v[48:63], v[204:207], v[110:113], v[48:63]
	v_mfma_f32_32x32x16_bf16 v[64:79], v[208:211], v[110:113], v[64:79]
	ds_read_b64_tr_b16 v[212:213], v179 offset:18432
	ds_read_b64_tr_b16 v[214:215], v179 offset:19584
	ds_read_b64_tr_b16 v[216:217], v179 offset:18496
	ds_read_b64_tr_b16 v[218:219], v179 offset:19648
	ds_read_b64_tr_b16 v[236:237], v179 offset:20736
	ds_read_b64_tr_b16 v[238:239], v179 offset:21888
	ds_read_b64_tr_b16 v[240:241], v179 offset:20800
	ds_read_b64_tr_b16 v[242:243], v179 offset:21952
	ds_read_b64_tr_b16 v[244:245], v179 offset:23040
	ds_read_b64_tr_b16 v[246:247], v179 offset:24192
	v_mov_b64_e32 v[220:221], 0
	s_nop 7
	v_pk_fma_f32 v[48:49], v[48:49], v[222:223], v[88:89] op_sel_hi:[1,0,0]
	v_pk_fma_f32 v[50:51], v[50:51], v[222:223], v[88:89] op_sel_hi:[1,0,0]
	v_pk_fma_f32 v[52:53], v[52:53], v[222:223], v[88:89] op_sel_hi:[1,0,0]
	v_pk_fma_f32 v[54:55], v[54:55], v[222:223], v[88:89] op_sel_hi:[1,0,0]
	v_pk_fma_f32 v[56:57], v[56:57], v[222:223], v[88:89] op_sel_hi:[1,0,0]
	v_pk_fma_f32 v[58:59], v[58:59], v[222:223], v[88:89] op_sel_hi:[1,0,0]
	v_pk_fma_f32 v[60:61], v[60:61], v[222:223], v[88:89] op_sel_hi:[1,0,0]
	v_pk_fma_f32 v[62:63], v[62:63], v[222:223], v[88:89] op_sel_hi:[1,0,0]
	v_exp_f32_e32 v48, v48
	v_exp_f32_e32 v49, v49
	v_exp_f32_e32 v50, v50
	v_exp_f32_e32 v51, v51
	v_exp_f32_e32 v52, v52
	v_exp_f32_e32 v53, v53
	v_exp_f32_e32 v54, v54
	v_exp_f32_e32 v55, v55
	v_exp_f32_e32 v56, v56
	v_exp_f32_e32 v57, v57
	v_exp_f32_e32 v58, v58
	v_exp_f32_e32 v59, v59
	v_exp_f32_e32 v60, v60
	v_exp_f32_e32 v61, v61
	v_exp_f32_e32 v62, v62
	v_exp_f32_e32 v63, v63
	v_pk_fma_f32 v[64:65], v[64:65], v[222:223], v[88:89] op_sel_hi:[1,0,0]
	v_pk_fma_f32 v[66:67], v[66:67], v[222:223], v[88:89] op_sel_hi:[1,0,0]
	v_pk_fma_f32 v[68:69], v[68:69], v[222:223], v[88:89] op_sel_hi:[1,0,0]
	v_pk_fma_f32 v[70:71], v[70:71], v[222:223], v[88:89] op_sel_hi:[1,0,0]
	v_pk_fma_f32 v[72:73], v[72:73], v[222:223], v[88:89] op_sel_hi:[1,0,0]
	v_pk_fma_f32 v[74:75], v[74:75], v[222:223], v[88:89] op_sel_hi:[1,0,0]
	v_pk_fma_f32 v[76:77], v[76:77], v[222:223], v[88:89] op_sel_hi:[1,0,0]
	v_pk_fma_f32 v[78:79], v[78:79], v[222:223], v[88:89] op_sel_hi:[1,0,0]
	v_exp_f32_e32 v64, v64
	v_exp_f32_e32 v65, v65
	v_exp_f32_e32 v66, v66
	v_exp_f32_e32 v67, v67
	v_exp_f32_e32 v68, v68
	v_exp_f32_e32 v69, v69
	v_exp_f32_e32 v70, v70
	v_exp_f32_e32 v71, v71
	v_exp_f32_e32 v72, v72
	v_exp_f32_e32 v73, v73
	v_exp_f32_e32 v74, v74
	v_exp_f32_e32 v75, v75
	v_exp_f32_e32 v76, v76
	v_exp_f32_e32 v77, v77
	v_exp_f32_e32 v78, v78
	v_exp_f32_e32 v79, v79
	v_pk_add_f32 v[220:221], v[48:49], v[220:221]
	v_pk_add_f32 v[220:221], v[50:51], v[220:221]
	v_pk_add_f32 v[220:221], v[52:53], v[220:221]
	v_pk_add_f32 v[220:221], v[54:55], v[220:221]
	v_pk_add_f32 v[220:221], v[56:57], v[220:221]
	v_pk_add_f32 v[220:221], v[58:59], v[220:221]
	v_pk_add_f32 v[220:221], v[60:61], v[220:221]
	v_pk_add_f32 v[220:221], v[62:63], v[220:221]
	v_cvt_pk_bf16_f32 v48, v48, v49
	v_cvt_pk_bf16_f32 v49, v50, v51
	v_cvt_pk_bf16_f32 v50, v52, v53
	v_cvt_pk_bf16_f32 v51, v54, v55
	v_cvt_pk_bf16_f32 v56, v56, v57
	v_cvt_pk_bf16_f32 v57, v58, v59
	v_cvt_pk_bf16_f32 v58, v60, v61
	v_cvt_pk_bf16_f32 v59, v62, v63
	v_pk_add_f32 v[220:221], v[64:65], v[220:221]
	v_pk_add_f32 v[220:221], v[66:67], v[220:221]
	v_pk_add_f32 v[220:221], v[68:69], v[220:221]
	v_pk_add_f32 v[220:221], v[70:71], v[220:221]
	v_pk_add_f32 v[220:221], v[72:73], v[220:221]
	v_pk_add_f32 v[220:221], v[74:75], v[220:221]
	v_pk_add_f32 v[220:221], v[76:77], v[220:221]
	v_pk_add_f32 v[220:221], v[78:79], v[220:221]
	v_cvt_pk_bf16_f32 v64, v64, v65
	v_cvt_pk_bf16_f32 v65, v66, v67
	v_cvt_pk_bf16_f32 v66, v68, v69
	v_cvt_pk_bf16_f32 v67, v70, v71
	v_cvt_pk_bf16_f32 v72, v72, v73
	v_cvt_pk_bf16_f32 v73, v74, v75
	v_cvt_pk_bf16_f32 v74, v76, v77
	v_cvt_pk_bf16_f32 v75, v78, v79
	v_add_f32_e32 v89, v89, v220
	v_add_f32_e32 v89, v89, v221
	s_waitcnt lgkmcnt(8)
	v_mfma_f32_32x32x16_bf16 v[32:47], v[212:215], v[48:51], v[32:47]
	ds_read_b64_tr_b16 v[248:249], v179 offset:23104
	ds_read_b64_tr_b16 v[250:251], v179 offset:24256
	s_waitcnt lgkmcnt(8)
	v_mfma_f32_32x32x16_bf16 v[16:31], v[216:219], v[48:51], v[16:31]
	ds_read_b64_tr_b16 v[212:213], v179 offset:25344
	ds_read_b64_tr_b16 v[214:215], v179 offset:26496
	s_waitcnt lgkmcnt(8)
	v_mfma_f32_32x32x16_bf16 v[32:47], v[236:239], v[56:59], v[32:47]
	ds_read_b64_tr_b16 v[216:217], v179 offset:25408
	ds_read_b64_tr_b16 v[218:219], v179 offset:26560
	s_waitcnt lgkmcnt(8)
	v_mfma_f32_32x32x16_bf16 v[16:31], v[240:243], v[56:59], v[16:31]
	s_waitcnt lgkmcnt(6)
	v_mfma_f32_32x32x16_bf16 v[32:47], v[244:247], v[64:67], v[32:47]
	s_waitcnt lgkmcnt(4)
	v_mfma_f32_32x32x16_bf16 v[16:31], v[248:251], v[64:67], v[16:31]
	s_waitcnt lgkmcnt(2)
	v_mfma_f32_32x32x16_bf16 v[32:47], v[212:215], v[72:75], v[32:47]
	s_waitcnt lgkmcnt(0)
	v_mfma_f32_32x32x16_bf16 v[16:31], v[216:219], v[72:75], v[16:31]
	s_branch .LBB0_399
.Lnsa_win_slow:
	v_add_u32_e32 v1, s91, v177
	ds_read_b128 v[2:5], v1 offset:4608
	ds_read_b128 v[6:9], v1
	ds_read_b128 v[10:13], v1 offset:32
	v_cmp_le_i32_e32 vcc, s0, v176
	v_cmp_ge_i32_e64 s[0:1], s2, v145
	s_waitcnt lgkmcnt(0)
	v_mfma_f32_32x32x16_bf16 v[48:63], v[2:5], v[98:101], 0
	ds_read_b128 v[2:5], v1 offset:4640
	s_and_b64 s[0:1], vcc, s[0:1]
	v_mfma_f32_32x32x16_bf16 v[64:79], v[6:9], v[98:101], 0
	v_mfma_f32_32x32x16_bf16 v[64:79], v[10:13], v[102:105], v[64:79]
	s_waitcnt lgkmcnt(0)
	v_mfma_f32_32x32x16_bf16 v[48:63], v[2:5], v[102:105], v[48:63]
	ds_read_b128 v[2:5], v1 offset:64
	ds_read_b128 v[6:9], v1 offset:4672
	s_waitcnt lgkmcnt(0)
	v_mfma_f32_32x32x16_bf16 v[64:79], v[2:5], v[106:109], v[64:79]
	v_mfma_f32_32x32x16_bf16 v[48:63], v[6:9], v[106:109], v[48:63]
	ds_read_b128 v[2:5], v1 offset:96
	ds_read_b128 v[6:9], v1 offset:4704
	s_waitcnt lgkmcnt(0)
	v_mfma_f32_32x32x16_bf16 v[64:79], v[2:5], v[110:113], v[64:79]
	v_mfma_f32_32x32x16_bf16 v[48:63], v[6:9], v[110:113], v[48:63]
	s_and_saveexec_b64 s[4:5], s[0:1]
	s_xor_b64 s[0:1], exec, s[4:5]
	s_cbranch_execz .LBB0_405
	v_mov_b32_e32 v88, s81
	s_nop 6
	v_fma_f32 v4, v66, s33, -v88
	v_exp_f32_e32 v12, v4
	v_fma_f32 v4, v67, s33, -v88
	v_exp_f32_e32 v13, v4
	v_fma_f32 v4, v68, s33, -v88
	v_exp_f32_e32 v94, v4
	v_fma_f32 v4, v69, s33, -v88
	v_exp_f32_e32 v95, v4
	v_fma_f32 v4, v70, s33, -v88
	v_exp_f32_e32 v130, v4
	v_fma_f32 v4, v71, s33, -v88
	v_exp_f32_e32 v131, v4
	v_fma_f32 v4, v72, s33, -v88
	v_exp_f32_e32 v6, v4
	v_fma_f32 v4, v73, s33, -v88
	v_exp_f32_e32 v7, v4
	v_fma_f32 v4, v74, s33, -v88
	v_exp_f32_e32 v10, v4
	v_fma_f32 v4, v75, s33, -v88
	v_exp_f32_e32 v11, v4
	v_fma_f32 v4, v76, s33, -v88
	v_exp_f32_e32 v92, v4
	v_fma_f32 v4, v77, s33, -v88
	v_exp_f32_e32 v93, v4
	v_fma_f32 v4, v78, s33, -v88
	v_fma_f32 v1, v64, s33, -v88
	v_exp_f32_e32 v128, v4
	v_fma_f32 v4, v79, s33, -v88
	v_exp_f32_e32 v2, v1
	v_fma_f32 v1, v65, s33, -v88
	v_exp_f32_e32 v129, v4
	v_fma_f32 v4, v48, s33, -v88
	v_exp_f32_e32 v3, v1
	v_exp_f32_e32 v4, v4
	v_fma_f32 v5, v49, s33, -v88
	v_exp_f32_e32 v5, v5
	v_fma_f32 v8, v50, s33, -v88
	v_exp_f32_e32 v8, v8
	v_fma_f32 v9, v51, s33, -v88
	v_exp_f32_e32 v9, v9
	v_fma_f32 v14, v52, s33, -v88
	v_add_f32_e32 v1, 0, v2
	v_exp_f32_e32 v14, v14
	v_fma_f32 v15, v53, s33, -v88
	v_mov_b32_e32 v48, v4
	v_mov_b32_e32 v49, v3
	v_exp_f32_e32 v15, v15
	v_pk_add_f32 v[48:49], v[48:49], v[0:1]
	v_mov_b32_e32 v50, v5
	v_mov_b32_e32 v51, v12
	v_fma_f32 v1, v54, s33, -v88
	v_pk_add_f32 v[48:49], v[50:51], v[48:49]
	v_mov_b32_e32 v50, v8
	v_mov_b32_e32 v51, v13
	v_exp_f32_e32 v136, v1
	v_fma_f32 v1, v55, s33, -v88
	v_pk_add_f32 v[48:49], v[50:51], v[48:49]
	v_mov_b32_e32 v50, v9
	v_mov_b32_e32 v51, v94
	v_exp_f32_e32 v137, v1
	v_fma_f32 v1, v56, s33, -v88
	v_pk_add_f32 v[48:49], v[50:51], v[48:49]
	v_mov_b32_e32 v50, v14
	v_mov_b32_e32 v51, v95
	v_exp_f32_e32 v96, v1
	v_fma_f32 v1, v57, s33, -v88
	v_pk_add_f32 v[48:49], v[50:51], v[48:49]
	v_mov_b32_e32 v50, v15
	v_mov_b32_e32 v51, v130
	v_exp_f32_e32 v97, v1
	v_fma_f32 v1, v58, s33, -v88
	v_pk_add_f32 v[48:49], v[50:51], v[48:49]
	v_exp_f32_e32 v132, v1
	v_fma_f32 v1, v59, s33, -v88
	v_mov_b32_e32 v50, v136
	v_mov_b32_e32 v51, v131
	v_exp_f32_e32 v133, v1
	v_fma_f32 v1, v60, s33, -v88
	v_pk_add_f32 v[48:49], v[50:51], v[48:49]
	v_mov_b32_e32 v50, v137
	v_mov_b32_e32 v51, v6
	v_exp_f32_e32 v134, v1
	v_fma_f32 v1, v61, s33, -v88
	v_pk_add_f32 v[48:49], v[50:51], v[48:49]
	v_mov_b32_e32 v50, v96
	v_mov_b32_e32 v51, v7
	v_exp_f32_e32 v135, v1
	v_pk_add_f32 v[48:49], v[50:51], v[48:49]
	v_mov_b32_e32 v50, v97
	v_mov_b32_e32 v51, v10
	v_pk_add_f32 v[48:49], v[50:51], v[48:49]
	v_mov_b32_e32 v50, v132
	v_mov_b32_e32 v51, v11
	v_fma_f32 v1, v62, s33, -v88
	v_pk_add_f32 v[48:49], v[50:51], v[48:49]
	v_mov_b32_e32 v50, v133
	v_mov_b32_e32 v51, v92
	v_exp_f32_e32 v138, v1
	v_pk_add_f32 v[48:49], v[50:51], v[48:49]
	v_mov_b32_e32 v50, v134
	v_mov_b32_e32 v51, v93
	v_pk_add_f32 v[48:49], v[50:51], v[48:49]
	v_mov_b32_e32 v50, v135
	v_mov_b32_e32 v51, v128
	v_pk_add_f32 v[48:49], v[50:51], v[48:49]
	v_mov_b32_e32 v139, v129
	v_pk_add_f32 v[140:141], v[138:139], v[48:49]
	v_fma_f32 v1, v63, s33, -v88
